# rw_post: the four mixing-bias loads issued together in the first column group's block; later groups read prefetched registers, their vmcnt(0) waits removed
# baseline (speedup 1.0000x reference)
; __device__ __forceinline__ f32x4 unpk4(u32x2 w) { return (f32x4){__uint_as_float(w.x << 16), __uint_as_float(w.x & 0xffff0000u), __uint_as_float(w.y << 16), __uint_as_float(w.y & 0xffff0000u)}; }
; __device__ __forceinline__ f32x4 sigm4(f32x4 x) { return (f32x4){sigm(x[0]), sigm(x[1]), sigm(x[2]), sigm(x[3])}; }
; __device__ __forceinline__ void rw_post(const bf16_t* Vg, const bf16_t* VF, const bf16_t* LO, const bf16_t* gbT, const bf16_t* vlbT, const float* v0, const bf16_t* WKV, const float* BON, const float* ln_w, const float* ln_b, bf16_t* Y, bf16_t* VFout) {
;     ...
;         for (int td = 0; td < 4; ++td) { f32x4 v4 = unpk4(vv[td]);
;             if (hasvf) { const f32x4 vf4 = unpk4(vf[td]); v4 = v4 + (vf4 - v4) * sigm4(*(const f32x4*)(v0 + cb + td * 16) + accv[td]); }
.LBB0_385:
	v_readlane_b32 s40, v253, 33
	v_lshlrev_b32_e32 v150, 2, v226
	v_mov_b32_e32 v151, v0
	v_readlane_b32 s54, v253, 47
	v_readlane_b32 s55, v253, 48
	v_lshlrev_b32_e32 v178, 16, v176
	v_and_b32_e32 v179, 0xffff0000, v176
	v_lshl_add_u64 v[142:143], s[54:55], 0, v[150:151]
	v_lshlrev_b32_e32 v176, 16, v177
	s_andn2_b64 vcc, exec, s[26:27]
	v_and_b32_e32 v177, 0xffff0000, v177
	v_readlane_b32 s41, v253, 34
	v_readlane_b32 s42, v253, 35
	v_readlane_b32 s43, v253, 36
	v_readlane_b32 s44, v253, 37
	v_readlane_b32 s45, v253, 38
	v_readlane_b32 s46, v253, 39
	v_readlane_b32 s47, v253, 40
	v_readlane_b32 s48, v253, 41
	v_readlane_b32 s49, v253, 42
	v_readlane_b32 s50, v253, 43
	v_readlane_b32 s51, v253, 44
	v_readlane_b32 s52, v253, 45
	v_readlane_b32 s53, v253, 46
	s_cbranch_vccnz .LBB0_387
	global_load_dwordx4 v[182:185], v[142:143], off
	global_load_dwordx4 v[238:241], v[142:143], off offset:64
	global_load_dwordx4 v[246:249], v[142:143], off offset:128
	global_load_dwordx2 v[242:243], v[142:143], off offset:192
	global_load_dwordx2 v[218:219], v[142:143], off offset:200
	v_lshlrev_b32_e32 v151, 16, v174
	v_and_b32_e32 v173, 0xffff0000, v174
	v_lshlrev_b32_e32 v174, 16, v175
	v_and_b32_e32 v175, 0xffff0000, v175
	v_sub_f32_e32 v175, v175, v177
	v_sub_f32_e32 v174, v174, v176
	s_waitcnt vmcnt(4)
	v_pk_add_f32 v[130:131], v[130:131], v[184:185]
	v_pk_add_f32 v[128:129], v[128:129], v[182:183]
	v_mul_f32_e32 v130, 0xbfb8aa3b, v130
	v_mul_f32_e32 v128, 0xbfb8aa3b, v128
	v_mul_f32_e32 v129, 0xbfb8aa3b, v129
	v_mul_f32_e32 v131, 0xbfb8aa3b, v131
	v_exp_f32_e32 v128, v128
	v_exp_f32_e32 v129, v129
	v_exp_f32_e32 v130, v130
	v_exp_f32_e32 v131, v131
	v_add_f32_e32 v128, 1.0, v128
	v_add_f32_e32 v129, 1.0, v129
	v_add_f32_e32 v130, 1.0, v130
	v_add_f32_e32 v131, 1.0, v131
	v_rcp_f32_e32 v128, v128
	v_rcp_f32_e32 v129, v129
	v_rcp_f32_e32 v130, v130
	v_rcp_f32_e32 v131, v131
	v_sub_f32_e32 v183, v173, v179
	v_sub_f32_e32 v182, v151, v178
	v_pk_fma_f32 v[178:179], v[182:183], v[128:129], v[178:179]
	v_pk_fma_f32 v[176:177], v[174:175], v[130:131], v[176:177]

; __device__ __forceinline__ f32x4 unpk4(u32x2 w) { return (f32x4){__uint_as_float(w.x << 16), __uint_as_float(w.x & 0xffff0000u), __uint_as_float(w.y << 16), __uint_as_float(w.y & 0xffff0000u)}; }
; __device__ __forceinline__ f32x4 sigm4(f32x4 x) { return (f32x4){sigm(x[0]), sigm(x[1]), sigm(x[2]), sigm(x[3])}; }
; __device__ __forceinline__ void rw_post(const bf16_t* Vg, const bf16_t* VF, const bf16_t* LO, const bf16_t* gbT, const bf16_t* vlbT, const float* v0, const bf16_t* WKV, const float* BON, const float* ln_w, const float* ln_b, bf16_t* Y, bf16_t* VFout) {
;     ...
;             if (hasvf) { const f32x4 vf4 = unpk4(vf[td]); v4 = v4 + (vf4 - v4) * sigm4(*(const f32x4*)(v0 + cb + td * 16) + accv[td]); }
.LBB0_389:
	v_lshlrev_b32_e32 v124, 16, v170
	v_and_b32_e32 v125, 0xffff0000, v170
	v_lshlrev_b32_e32 v126, 16, v171
	s_andn2_b64 vcc, exec, s[26:27]
	v_and_b32_e32 v127, 0xffff0000, v171
	s_cbranch_vccnz .LBB0_391
	v_lshlrev_b32_e32 v1, 16, v168
	v_and_b32_e32 v129, 0xffff0000, v168
	v_lshlrev_b32_e32 v145, 16, v169
	v_and_b32_e32 v151, 0xffff0000, v169
	v_sub_f32_e32 v169, v151, v127
	v_sub_f32_e32 v168, v145, v126
	v_pk_add_f32 v[122:123], v[122:123], v[240:241]
	v_pk_add_f32 v[120:121], v[120:121], v[238:239]
	v_mul_f32_e32 v122, 0xbfb8aa3b, v122
	v_mul_f32_e32 v120, 0xbfb8aa3b, v120
	v_mul_f32_e32 v121, 0xbfb8aa3b, v121
	v_mul_f32_e32 v123, 0xbfb8aa3b, v123
	v_exp_f32_e32 v120, v120
	v_exp_f32_e32 v121, v121
	v_exp_f32_e32 v122, v122
	v_exp_f32_e32 v123, v123
	v_add_f32_e32 v120, 1.0, v120
	v_add_f32_e32 v121, 1.0, v121
	v_add_f32_e32 v122, 1.0, v122
	v_add_f32_e32 v123, 1.0, v123
	v_rcp_f32_e32 v120, v120
	v_rcp_f32_e32 v121, v121
	v_rcp_f32_e32 v122, v122
	v_rcp_f32_e32 v123, v123
	v_sub_f32_e32 v171, v129, v125
	v_sub_f32_e32 v170, v1, v124
	v_pk_fma_f32 v[124:125], v[170:171], v[120:121], v[124:125]
	v_pk_fma_f32 v[126:127], v[168:169], v[122:123], v[126:127]

; __device__ __forceinline__ f32x4 unpk4(u32x2 w) { return (f32x4){__uint_as_float(w.x << 16), __uint_as_float(w.x & 0xffff0000u), __uint_as_float(w.y << 16), __uint_as_float(w.y & 0xffff0000u)}; }
; __device__ __forceinline__ f32x4 sigm4(f32x4 x) { return (f32x4){sigm(x[0]), sigm(x[1]), sigm(x[2]), sigm(x[3])}; }
; __device__ __forceinline__ void rw_post(const bf16_t* Vg, const bf16_t* VF, const bf16_t* LO, const bf16_t* gbT, const bf16_t* vlbT, const float* v0, const bf16_t* WKV, const float* BON, const float* ln_w, const float* ln_b, bf16_t* Y, bf16_t* VFout) {
;     ...
;             if (hasvf) { const f32x4 vf4 = unpk4(vf[td]); v4 = v4 + (vf4 - v4) * sigm4(*(const f32x4*)(v0 + cb + td * 16) + accv[td]); }
.LBB0_393:
	v_lshlrev_b32_e32 v116, 16, v166
	v_and_b32_e32 v117, 0xffff0000, v166
	v_lshlrev_b32_e32 v118, 16, v167
	s_andn2_b64 vcc, exec, s[26:27]
	v_and_b32_e32 v119, 0xffff0000, v167
	s_cbranch_vccnz .LBB0_395
	v_lshlrev_b32_e32 v1, 16, v164
	v_and_b32_e32 v148, 0xffff0000, v164
	v_lshlrev_b32_e32 v146, 16, v165
	v_and_b32_e32 v147, 0xffff0000, v165
	v_sub_f32_e32 v147, v147, v119
	v_sub_f32_e32 v146, v146, v118
	v_pk_add_f32 v[114:115], v[114:115], v[248:249]
	v_pk_add_f32 v[112:113], v[112:113], v[246:247]
	v_mul_f32_e32 v114, 0xbfb8aa3b, v114
	v_mul_f32_e32 v112, 0xbfb8aa3b, v112
	v_mul_f32_e32 v113, 0xbfb8aa3b, v113
	v_mul_f32_e32 v115, 0xbfb8aa3b, v115
	v_exp_f32_e32 v112, v112
	v_exp_f32_e32 v113, v113
	v_exp_f32_e32 v114, v114
	v_exp_f32_e32 v115, v115
	v_add_f32_e32 v112, 1.0, v112
	v_add_f32_e32 v113, 1.0, v113
	v_add_f32_e32 v114, 1.0, v114
	v_add_f32_e32 v115, 1.0, v115
	v_rcp_f32_e32 v112, v112
	v_rcp_f32_e32 v113, v113
	v_rcp_f32_e32 v114, v114
	v_rcp_f32_e32 v115, v115
	v_sub_f32_e32 v125, v148, v117
	v_sub_f32_e32 v124, v1, v116
	v_pk_fma_f32 v[116:117], v[124:125], v[112:113], v[116:117]
	v_pk_fma_f32 v[118:119], v[146:147], v[114:115], v[118:119]

; __device__ __forceinline__ f32x4 unpk4(u32x2 w) { return (f32x4){__uint_as_float(w.x << 16), __uint_as_float(w.x & 0xffff0000u), __uint_as_float(w.y << 16), __uint_as_float(w.y & 0xffff0000u)}; }
; __device__ __forceinline__ f32x4 sigm4(f32x4 x) { return (f32x4){sigm(x[0]), sigm(x[1]), sigm(x[2]), sigm(x[3])}; }
; __device__ __forceinline__ void rw_post(const bf16_t* Vg, const bf16_t* VF, const bf16_t* LO, const bf16_t* gbT, const bf16_t* vlbT, const float* v0, const bf16_t* WKV, const float* BON, const float* ln_w, const float* ln_b, bf16_t* Y, bf16_t* VFout) {
;     ...
;             if (hasvf) { const f32x4 vf4 = unpk4(vf[td]); v4 = v4 + (vf4 - v4) * sigm4(*(const f32x4*)(v0 + cb + td * 16) + accv[td]); }
.LBB0_397:
	v_lshlrev_b32_e32 v108, 16, v162
	v_and_b32_e32 v109, 0xffff0000, v162
	v_lshlrev_b32_e32 v110, 16, v163
	s_andn2_b64 vcc, exec, s[26:27]
	v_and_b32_e32 v111, 0xffff0000, v163
	s_cbranch_vccnz .LBB0_353
	v_lshlrev_b32_e32 v1, 16, v2
	v_and_b32_e32 v116, 0xffff0000, v2
	v_lshlrev_b32_e32 v2, 16, v3
	v_and_b32_e32 v3, 0xffff0000, v3
	v_sub_f32_e32 v3, v3, v111
	v_sub_f32_e32 v2, v2, v110
	v_pk_add_f32 v[106:107], v[106:107], v[218:219]
	v_pk_add_f32 v[104:105], v[104:105], v[242:243]
	v_mul_f32_e32 v106, 0xbfb8aa3b, v106
	v_mul_f32_e32 v104, 0xbfb8aa3b, v104
	v_mul_f32_e32 v105, 0xbfb8aa3b, v105
	v_mul_f32_e32 v107, 0xbfb8aa3b, v107
	v_exp_f32_e32 v104, v104
	v_exp_f32_e32 v105, v105
	v_exp_f32_e32 v106, v106
	v_exp_f32_e32 v107, v107
	v_add_f32_e32 v104, 1.0, v104
	v_add_f32_e32 v105, 1.0, v105
	v_add_f32_e32 v106, 1.0, v106
	v_add_f32_e32 v107, 1.0, v107
	v_rcp_f32_e32 v104, v104
	v_rcp_f32_e32 v105, v105
	v_rcp_f32_e32 v106, v106
	v_rcp_f32_e32 v107, v107
	v_sub_f32_e32 v113, v116, v109
	v_sub_f32_e32 v112, v1, v108
	v_pk_fma_f32 v[108:109], v[112:113], v[104:105], v[108:109]
	v_pk_fma_f32 v[110:111], v[2:3], v[106:107], v[110:111]
	s_branch .LBB0_353
